# ff2 epilogue second pass: gain vector hoisted out of the 8 row steps; every pair of half-sector f32 output stores replaced by two full-sector stores (lane quads rotated with v_permlane16_swap + v_perm
# speedup vs baseline: 1.0206x; 1.0009x over previous
;   DI void operator()(g8::Acc& acc, int pm, int pn, int wr, int wc, int fr, int fq) const {
;     ...
;     __syncthreads();
; #pragma unroll
;     for (int ai = 0; ai < 2; ++ai)
; #pragma unroll
;       for (int m = 0; m < 4; ++m) {
;         const int row = pm * BM + ai * HALF + wr * 64 + m * 16 + fr;
;         const float rs = rsqrtf(__hip_atomic_load(ssq + row, __ATOMIC_RELAXED, __HIP_MEMORY_SCOPE_AGENT) * (1.0f / DM) + RMS_EPS);
; #pragma unroll
;         for (int bj = 0; bj < 2; ++bj) {
;           const int col8 = pn * BM + wc * 64 + bj * 32 + fq * 8; const unsigned eo = (unsigned)row * DM + (unsigned)col8;
;           gst<f32x4>(outf, eo * 4u, acc[ai][bj][m][0] * rs * gld<f32x4>(g, (unsigned)col8 * 4u));
;           gst<f32x4>(outf, eo * 4u + 16u, acc[ai][bj][m][1] * rs * gld<f32x4>(g, (unsigned)col8 * 4u + 16u));
;         }
;       }
.LBB0_930:
	s_or_b64 exec, exec, s[42:43]
	v_mbcnt_lo_u32_b32 v202, -1, 0
	v_mbcnt_hi_u32_b32 v202, -1, v202
	v_and_b32_e32 v202, 48, v202
	v_lshl_add_u64 v[164:165], v[140:141], 2, s[16:17]
	s_barrier
	global_load_dword v168, v[164:165], off sc1
	v_lshl_or_b32 v141, s38, 10, v158
	global_load_dwordx4 v[176:179], v141, s[70:71]
	global_load_dwordx4 v[180:183], v141, s[70:71] offset:16
	global_load_dwordx4 v[184:187], v141, s[70:71] offset:128
	global_load_dwordx4 v[188:191], v141, s[70:71] offset:144
	v_lshl_add_u64 v[200:201], v[116:117], 2, s[16:17]
	global_load_dword v193, v[200:201], off sc1
	v_lshl_add_u64 v[200:201], v[100:101], 2, s[16:17]
	global_load_dword v194, v[200:201], off sc1
	v_lshl_add_u64 v[200:201], v[84:85], 2, s[16:17]
	global_load_dword v195, v[200:201], off sc1
	v_lshl_add_u64 v[200:201], v[68:69], 2, s[16:17]
	global_load_dword v196, v[200:201], off sc1
	v_lshl_add_u64 v[200:201], v[52:53], 2, s[16:17]
	global_load_dword v197, v[200:201], off sc1
	v_lshl_add_u64 v[200:201], v[36:37], 2, s[16:17]
	global_load_dword v198, v[200:201], off sc1
	v_lshl_add_u64 v[200:201], v[20:21], 2, s[16:17]
	global_load_dword v199, v[200:201], off sc1
	s_waitcnt vmcnt(0)
	s_mov_b64 s[0:1], -1
	v_fmamk_f32 v168, v168, 0x3a800000, v163
	v_mul_f32_e32 v169, 0x4b800000, v168
	v_cmp_gt_f32_e32 vcc, s51, v168
	s_nop 1
	v_cndmask_b32_e32 v168, v168, v169, vcc
	v_rsq_f32_e32 v168, v168
	v_lshlrev_b32_e32 v169, 12, v140
	v_add_u32_e32 v170, v141, v169
	v_mul_f32_e32 v140, 0x45800000, v168
	v_cndmask_b32_e32 v140, v168, v140, vcc
	v_pk_mul_f32 v[142:143], v[142:143], v[140:141] op_sel_hi:[1,0]
	v_pk_mul_f32 v[126:127], v[126:127], v[140:141] op_sel_hi:[1,0]
	v_pk_mul_f32 v[164:165], v[176:177], v[142:143]
	v_pk_mul_f32 v[166:167], v[178:179], v[126:127]
	v_mov_b32_e32 v204, v164
	v_mov_b32_e32 v205, v165
	v_mov_b32_e32 v206, v166
	v_mov_b32_e32 v207, v167
	v_pk_mul_f32 v[126:127], v[122:123], v[140:141] op_sel_hi:[1,0]
	v_pk_mul_f32 v[122:123], v[124:125], v[140:141] op_sel_hi:[1,0]
	v_pk_mul_f32 v[142:143], v[118:119], v[140:141] op_sel_hi:[1,0]
	v_pk_mul_f32 v[118:119], v[120:121], v[140:141] op_sel_hi:[1,0]
	v_pk_mul_f32 v[114:115], v[114:115], v[140:141] op_sel_hi:[1,0]
	v_pk_mul_f32 v[112:113], v[112:113], v[140:141] op_sel_hi:[1,0]
	v_pk_mul_f32 v[122:123], v[180:181], v[122:123]
	v_pk_mul_f32 v[124:125], v[182:183], v[126:127]
	s_nop 1
	v_permlane16_swap_b32_e32 v204, v122
	v_permlane16_swap_b32_e32 v205, v123
	v_permlane16_swap_b32_e32 v206, v124
	v_permlane16_swap_b32_e32 v207, v125
	v_permlane32_swap_b32_e32 v204, v122
	v_permlane32_swap_b32_e32 v205, v123
	v_permlane32_swap_b32_e32 v206, v124
	v_permlane32_swap_b32_e32 v207, v125
	v_sub_u32_e32 v203, v170, v202
	global_store_dwordx4 v203, v[204:207], s[72:73]
	global_store_dwordx4 v203, v[122:125], s[72:73] offset:64
	s_nop 1
	v_pk_mul_f32 v[118:119], v[184:185], v[118:119]
	v_or_b32_e32 v122, 0x80, v141
	v_add_u32_e32 v123, v122, v169
	v_pk_mul_f32 v[120:121], v[186:187], v[142:143]
	v_mov_b32_e32 v204, v118
	v_mov_b32_e32 v205, v119
	v_mov_b32_e32 v206, v120
	v_mov_b32_e32 v207, v121
	v_pk_mul_f32 v[112:113], v[188:189], v[112:113]
	v_pk_mul_f32 v[114:115], v[190:191], v[114:115]
	s_nop 1
	v_permlane16_swap_b32_e32 v204, v112
	v_permlane16_swap_b32_e32 v205, v113
	v_permlane16_swap_b32_e32 v206, v114
	v_permlane16_swap_b32_e32 v207, v115
	v_permlane32_swap_b32_e32 v204, v112
	v_permlane32_swap_b32_e32 v205, v113
	v_permlane32_swap_b32_e32 v206, v114
	v_permlane32_swap_b32_e32 v207, v115
	v_sub_u32_e32 v203, v123, v202
	global_store_dwordx4 v203, v[204:207], s[72:73]
	global_store_dwordx4 v203, v[112:115], s[72:73] offset:64
	s_nop 1
	s_nop 0
	v_lshlrev_b32_e32 v120, 12, v116
	v_add_u32_e32 v121, v120, v141
	v_fmamk_f32 v117, v193, 0x3a800000, v163
	v_mul_f32_e32 v118, 0x4b800000, v117
	v_cmp_gt_f32_e32 vcc, s51, v117
	s_nop 1
	v_cndmask_b32_e32 v117, v117, v118, vcc
	v_rsq_f32_e32 v117, v117
	s_nop 0
	v_mul_f32_e32 v116, 0x45800000, v117
	v_cndmask_b32_e32 v116, v117, v116, vcc
	v_pk_mul_f32 v[118:119], v[144:145], v[116:117] op_sel_hi:[1,0]
	v_pk_mul_f32 v[110:111], v[110:111], v[116:117] op_sel_hi:[1,0]
	v_pk_mul_f32 v[112:113], v[176:177], v[118:119]
	v_pk_mul_f32 v[114:115], v[178:179], v[110:111]
	v_mov_b32_e32 v204, v112
	v_mov_b32_e32 v205, v113
	v_mov_b32_e32 v206, v114
	v_mov_b32_e32 v207, v115
	v_pk_mul_f32 v[98:99], v[98:99], v[116:117] op_sel_hi:[1,0]
	v_pk_mul_f32 v[114:115], v[106:107], v[116:117] op_sel_hi:[1,0]
	v_pk_mul_f32 v[106:107], v[108:109], v[116:117] op_sel_hi:[1,0]
	v_pk_mul_f32 v[96:97], v[96:97], v[116:117] op_sel_hi:[1,0]
	v_pk_mul_f32 v[106:107], v[180:181], v[106:107]
	v_pk_mul_f32 v[108:109], v[182:183], v[114:115]
	s_nop 1
	v_permlane16_swap_b32_e32 v204, v106
	v_permlane16_swap_b32_e32 v205, v107
	v_permlane16_swap_b32_e32 v206, v108
	v_permlane16_swap_b32_e32 v207, v109
	v_permlane32_swap_b32_e32 v204, v106
	v_permlane32_swap_b32_e32 v205, v107
	v_permlane32_swap_b32_e32 v206, v108
	v_permlane32_swap_b32_e32 v207, v109
	v_sub_u32_e32 v203, v121, v202
	global_store_dwordx4 v203, v[204:207], s[72:73]
	global_store_dwordx4 v203, v[106:109], s[72:73] offset:64
	s_nop 1
	v_pk_mul_f32 v[110:111], v[102:103], v[116:117] op_sel_hi:[1,0]
	v_pk_mul_f32 v[102:103], v[104:105], v[116:117] op_sel_hi:[1,0]
	v_add_u32_e32 v112, v122, v120
	v_pk_mul_f32 v[102:103], v[184:185], v[102:103]
	v_pk_mul_f32 v[104:105], v[186:187], v[110:111]
	v_mov_b32_e32 v204, v102
	v_mov_b32_e32 v205, v103
	v_mov_b32_e32 v206, v104
	v_mov_b32_e32 v207, v105
	v_pk_mul_f32 v[96:97], v[188:189], v[96:97]
	v_pk_mul_f32 v[98:99], v[190:191], v[98:99]
	s_nop 1
	v_permlane16_swap_b32_e32 v204, v96
;   DI void operator()(g8::Acc& acc, int pm, int pn, int wr, int wc, int fr, int fq) const {
;     ...
;     for (int ai = 0; ai < 2; ++ai)
; #pragma unroll
;       for (int m = 0; m < 4; ++m) {
;         const int row = pm * BM + ai * HALF + wr * 64 + m * 16 + fr;
;         const float rs = rsqrtf(__hip_atomic_load(ssq + row, __ATOMIC_RELAXED, __HIP_MEMORY_SCOPE_AGENT) * (1.0f / DM) + RMS_EPS);
; #pragma unroll
;         for (int bj = 0; bj < 2; ++bj) {
;           const int col8 = pn * BM + wc * 64 + bj * 32 + fq * 8; const unsigned eo = (unsigned)row * DM + (unsigned)col8;
;           gst<f32x4>(outf, eo * 4u, acc[ai][bj][m][0] * rs * gld<f32x4>(g, (unsigned)col8 * 4u));
;           gst<f32x4>(outf, eo * 4u + 16u, acc[ai][bj][m][1] * rs * gld<f32x4>(g, (unsigned)col8 * 4u + 16u));
;         }
;       }
	v_permlane16_swap_b32_e32 v205, v97
	v_permlane16_swap_b32_e32 v206, v98
	v_permlane16_swap_b32_e32 v207, v99
	v_permlane32_swap_b32_e32 v204, v96
	v_permlane32_swap_b32_e32 v205, v97
	v_permlane32_swap_b32_e32 v206, v98
	v_permlane32_swap_b32_e32 v207, v99
	v_sub_u32_e32 v203, v112, v202
	global_store_dwordx4 v203, v[204:207], s[72:73]
	global_store_dwordx4 v203, v[96:99], s[72:73] offset:64
	s_nop 1
	s_nop 0
	v_lshlrev_b32_e32 v104, 12, v100
	v_add_u32_e32 v105, v104, v141
	v_fmamk_f32 v101, v194, 0x3a800000, v163
	v_mul_f32_e32 v102, 0x4b800000, v101
	v_cmp_gt_f32_e32 vcc, s51, v101
	s_nop 1
	v_cndmask_b32_e32 v101, v101, v102, vcc
	v_rsq_f32_e32 v101, v101
	s_nop 0
	v_mul_f32_e32 v100, 0x45800000, v101
	v_cndmask_b32_e32 v100, v101, v100, vcc
	v_pk_mul_f32 v[102:103], v[146:147], v[100:101] op_sel_hi:[1,0]
	v_pk_mul_f32 v[94:95], v[94:95], v[100:101] op_sel_hi:[1,0]
	v_pk_mul_f32 v[96:97], v[176:177], v[102:103]
	v_pk_mul_f32 v[98:99], v[178:179], v[94:95]
	v_mov_b32_e32 v204, v96
	v_mov_b32_e32 v205, v97
	v_mov_b32_e32 v206, v98
	v_mov_b32_e32 v207, v99
	v_pk_mul_f32 v[82:83], v[82:83], v[100:101] op_sel_hi:[1,0]
	v_pk_mul_f32 v[98:99], v[90:91], v[100:101] op_sel_hi:[1,0]
	v_pk_mul_f32 v[90:91], v[92:93], v[100:101] op_sel_hi:[1,0]
	v_pk_mul_f32 v[80:81], v[80:81], v[100:101] op_sel_hi:[1,0]
	v_pk_mul_f32 v[90:91], v[180:181], v[90:91]
	v_pk_mul_f32 v[92:93], v[182:183], v[98:99]
	s_nop 1
	v_permlane16_swap_b32_e32 v204, v90
	v_permlane16_swap_b32_e32 v205, v91
	v_permlane16_swap_b32_e32 v206, v92
	v_permlane16_swap_b32_e32 v207, v93
	v_permlane32_swap_b32_e32 v204, v90
	v_permlane32_swap_b32_e32 v205, v91
	v_permlane32_swap_b32_e32 v206, v92
	v_permlane32_swap_b32_e32 v207, v93
	v_sub_u32_e32 v203, v105, v202
	global_store_dwordx4 v203, v[204:207], s[72:73]
	global_store_dwordx4 v203, v[90:93], s[72:73] offset:64
	s_nop 1
	v_pk_mul_f32 v[94:95], v[86:87], v[100:101] op_sel_hi:[1,0]
	v_pk_mul_f32 v[86:87], v[88:89], v[100:101] op_sel_hi:[1,0]
	v_add_u32_e32 v96, v122, v104
	v_pk_mul_f32 v[86:87], v[184:185], v[86:87]
	v_pk_mul_f32 v[88:89], v[186:187], v[94:95]
	v_mov_b32_e32 v204, v86
	v_mov_b32_e32 v205, v87
	v_mov_b32_e32 v206, v88
	v_mov_b32_e32 v207, v89
	v_pk_mul_f32 v[80:81], v[188:189], v[80:81]
	v_pk_mul_f32 v[82:83], v[190:191], v[82:83]
	s_nop 1
	v_permlane16_swap_b32_e32 v204, v80
	v_permlane16_swap_b32_e32 v205, v81
	v_permlane16_swap_b32_e32 v206, v82
	v_permlane16_swap_b32_e32 v207, v83
	v_permlane32_swap_b32_e32 v204, v80
	v_permlane32_swap_b32_e32 v205, v81
	v_permlane32_swap_b32_e32 v206, v82
	v_permlane32_swap_b32_e32 v207, v83
	v_sub_u32_e32 v203, v96, v202
	global_store_dwordx4 v203, v[204:207], s[72:73]
	global_store_dwordx4 v203, v[80:83], s[72:73] offset:64
	s_nop 1
	s_nop 0
	v_lshlrev_b32_e32 v88, 12, v84
	v_add_u32_e32 v89, v88, v141
	v_fmamk_f32 v85, v195, 0x3a800000, v163
	v_mul_f32_e32 v86, 0x4b800000, v85
	v_cmp_gt_f32_e32 vcc, s51, v85
	s_nop 1
	v_cndmask_b32_e32 v85, v85, v86, vcc
	v_rsq_f32_e32 v85, v85
	s_nop 0
	v_mul_f32_e32 v84, 0x45800000, v85
	v_cndmask_b32_e32 v84, v85, v84, vcc
	v_pk_mul_f32 v[86:87], v[148:149], v[84:85] op_sel_hi:[1,0]
	v_pk_mul_f32 v[78:79], v[78:79], v[84:85] op_sel_hi:[1,0]
	v_pk_mul_f32 v[80:81], v[176:177], v[86:87]
	v_pk_mul_f32 v[82:83], v[178:179], v[78:79]
	v_mov_b32_e32 v204, v80
	v_mov_b32_e32 v205, v81
	v_mov_b32_e32 v206, v82
	v_mov_b32_e32 v207, v83
	v_pk_mul_f32 v[66:67], v[66:67], v[84:85] op_sel_hi:[1,0]
	v_pk_mul_f32 v[82:83], v[74:75], v[84:85] op_sel_hi:[1,0]
	v_pk_mul_f32 v[74:75], v[76:77], v[84:85] op_sel_hi:[1,0]
	v_pk_mul_f32 v[64:65], v[64:65], v[84:85] op_sel_hi:[1,0]
	v_pk_mul_f32 v[74:75], v[180:181], v[74:75]
	v_pk_mul_f32 v[76:77], v[182:183], v[82:83]
	s_nop 1
	v_permlane16_swap_b32_e32 v204, v74
	v_permlane16_swap_b32_e32 v205, v75
	v_permlane16_swap_b32_e32 v206, v76
	v_permlane16_swap_b32_e32 v207, v77
	v_permlane32_swap_b32_e32 v204, v74
	v_permlane32_swap_b32_e32 v205, v75
	v_permlane32_swap_b32_e32 v206, v76
	v_permlane32_swap_b32_e32 v207, v77
	v_sub_u32_e32 v203, v89, v202
	global_store_dwordx4 v203, v[204:207], s[72:73]
	global_store_dwordx4 v203, v[74:77], s[72:73] offset:64
	s_nop 1
	v_pk_mul_f32 v[78:79], v[70:71], v[84:85] op_sel_hi:[1,0]
	v_pk_mul_f32 v[70:71], v[72:73], v[84:85] op_sel_hi:[1,0]
	v_add_u32_e32 v80, v122, v88
	v_pk_mul_f32 v[70:71], v[184:185], v[70:71]
	v_pk_mul_f32 v[72:73], v[186:187], v[78:79]
	v_mov_b32_e32 v204, v70
	v_mov_b32_e32 v205, v71
	v_mov_b32_e32 v206, v72
	v_mov_b32_e32 v207, v73
	v_pk_mul_f32 v[64:65], v[188:189], v[64:65]
	v_pk_mul_f32 v[66:67], v[190:191], v[66:67]
	s_nop 1
	v_permlane16_swap_b32_e32 v204, v64
	v_permlane16_swap_b32_e32 v205, v65
	v_permlane16_swap_b32_e32 v206, v66
	v_permlane16_swap_b32_e32 v207, v67
	v_permlane32_swap_b32_e32 v204, v64
	v_permlane32_swap_b32_e32 v205, v65
	v_permlane32_swap_b32_e32 v206, v66
	v_permlane32_swap_b32_e32 v207, v67
	v_sub_u32_e32 v203, v80, v202
	global_store_dwordx4 v203, v[204:207], s[72:73]
	global_store_dwordx4 v203, v[64:67], s[72:73] offset:64
	s_nop 1
	s_nop 0
	v_lshlrev_b32_e32 v72, 12, v68
	v_add_u32_e32 v73, v72, v141
	v_fmamk_f32 v69, v196, 0x3a800000, v163
	v_mul_f32_e32 v70, 0x4b800000, v69
	v_cmp_gt_f32_e32 vcc, s51, v69
	s_nop 1
	v_cndmask_b32_e32 v69, v69, v70, vcc
	v_rsq_f32_e32 v69, v69
	s_nop 0
	v_mul_f32_e32 v68, 0x45800000, v69
	v_cndmask_b32_e32 v68, v69, v68, vcc
	v_pk_mul_f32 v[70:71], v[150:151], v[68:69] op_sel_hi:[1,0]
	v_pk_mul_f32 v[62:63], v[62:63], v[68:69] op_sel_hi:[1,0]
	v_pk_mul_f32 v[64:65], v[176:177], v[70:71]
	v_pk_mul_f32 v[66:67], v[178:179], v[62:63]
	v_mov_b32_e32 v204, v64
	v_mov_b32_e32 v205, v65
;   DI void operator()(g8::Acc& acc, int pm, int pn, int wr, int wc, int fr, int fq) const {
;     ...
;     for (int ai = 0; ai < 2; ++ai)
; #pragma unroll
;       for (int m = 0; m < 4; ++m) {
;         const int row = pm * BM + ai * HALF + wr * 64 + m * 16 + fr;
;         const float rs = rsqrtf(__hip_atomic_load(ssq + row, __ATOMIC_RELAXED, __HIP_MEMORY_SCOPE_AGENT) * (1.0f / DM) + RMS_EPS);
; #pragma unroll
;         for (int bj = 0; bj < 2; ++bj) {
;           const int col8 = pn * BM + wc * 64 + bj * 32 + fq * 8; const unsigned eo = (unsigned)row * DM + (unsigned)col8;
;           gst<f32x4>(outf, eo * 4u, acc[ai][bj][m][0] * rs * gld<f32x4>(g, (unsigned)col8 * 4u));
;           gst<f32x4>(outf, eo * 4u + 16u, acc[ai][bj][m][1] * rs * gld<f32x4>(g, (unsigned)col8 * 4u + 16u));
;         }
;       }
	v_mov_b32_e32 v206, v66
	v_mov_b32_e32 v207, v67
	v_pk_mul_f32 v[50:51], v[50:51], v[68:69] op_sel_hi:[1,0]
	v_pk_mul_f32 v[66:67], v[58:59], v[68:69] op_sel_hi:[1,0]
	v_pk_mul_f32 v[58:59], v[60:61], v[68:69] op_sel_hi:[1,0]
	v_pk_mul_f32 v[48:49], v[48:49], v[68:69] op_sel_hi:[1,0]
	v_pk_mul_f32 v[58:59], v[180:181], v[58:59]
	v_pk_mul_f32 v[60:61], v[182:183], v[66:67]
	s_nop 1
	v_permlane16_swap_b32_e32 v204, v58
	v_permlane16_swap_b32_e32 v205, v59
	v_permlane16_swap_b32_e32 v206, v60
	v_permlane16_swap_b32_e32 v207, v61
	v_permlane32_swap_b32_e32 v204, v58
	v_permlane32_swap_b32_e32 v205, v59
	v_permlane32_swap_b32_e32 v206, v60
	v_permlane32_swap_b32_e32 v207, v61
	v_sub_u32_e32 v203, v73, v202
	global_store_dwordx4 v203, v[204:207], s[72:73]
	global_store_dwordx4 v203, v[58:61], s[72:73] offset:64
	s_nop 1
	v_pk_mul_f32 v[62:63], v[54:55], v[68:69] op_sel_hi:[1,0]
	v_pk_mul_f32 v[54:55], v[56:57], v[68:69] op_sel_hi:[1,0]
	v_add_u32_e32 v64, v122, v72
	v_pk_mul_f32 v[54:55], v[184:185], v[54:55]
	v_pk_mul_f32 v[56:57], v[186:187], v[62:63]
	v_mov_b32_e32 v204, v54
	v_mov_b32_e32 v205, v55
	v_mov_b32_e32 v206, v56
	v_mov_b32_e32 v207, v57
	v_pk_mul_f32 v[48:49], v[188:189], v[48:49]
	v_pk_mul_f32 v[50:51], v[190:191], v[50:51]
	s_nop 1
	v_permlane16_swap_b32_e32 v204, v48
	v_permlane16_swap_b32_e32 v205, v49
	v_permlane16_swap_b32_e32 v206, v50
	v_permlane16_swap_b32_e32 v207, v51
	v_permlane32_swap_b32_e32 v204, v48
	v_permlane32_swap_b32_e32 v205, v49
	v_permlane32_swap_b32_e32 v206, v50
	v_permlane32_swap_b32_e32 v207, v51
	v_sub_u32_e32 v203, v64, v202
	global_store_dwordx4 v203, v[204:207], s[72:73]
	global_store_dwordx4 v203, v[48:51], s[72:73] offset:64
	s_nop 1
	s_nop 0
	v_lshlrev_b32_e32 v56, 12, v52
	v_add_u32_e32 v57, v56, v141
	v_fmamk_f32 v53, v197, 0x3a800000, v163
	v_mul_f32_e32 v54, 0x4b800000, v53
	v_cmp_gt_f32_e32 vcc, s51, v53
	s_nop 1
	v_cndmask_b32_e32 v53, v53, v54, vcc
	v_rsq_f32_e32 v53, v53
	s_nop 0
	v_mul_f32_e32 v52, 0x45800000, v53
	v_cndmask_b32_e32 v52, v53, v52, vcc
	v_pk_mul_f32 v[54:55], v[152:153], v[52:53] op_sel_hi:[1,0]
	v_pk_mul_f32 v[46:47], v[46:47], v[52:53] op_sel_hi:[1,0]
	v_pk_mul_f32 v[48:49], v[176:177], v[54:55]
	v_pk_mul_f32 v[50:51], v[178:179], v[46:47]
	v_mov_b32_e32 v204, v48
	v_mov_b32_e32 v205, v49
	v_mov_b32_e32 v206, v50
	v_mov_b32_e32 v207, v51
	v_pk_mul_f32 v[34:35], v[34:35], v[52:53] op_sel_hi:[1,0]
	v_pk_mul_f32 v[50:51], v[42:43], v[52:53] op_sel_hi:[1,0]
	v_pk_mul_f32 v[42:43], v[44:45], v[52:53] op_sel_hi:[1,0]
	v_pk_mul_f32 v[32:33], v[32:33], v[52:53] op_sel_hi:[1,0]
	v_pk_mul_f32 v[42:43], v[180:181], v[42:43]
	v_pk_mul_f32 v[44:45], v[182:183], v[50:51]
	s_nop 1
	v_permlane16_swap_b32_e32 v204, v42
	v_permlane16_swap_b32_e32 v205, v43
	v_permlane16_swap_b32_e32 v206, v44
	v_permlane16_swap_b32_e32 v207, v45
	v_permlane32_swap_b32_e32 v204, v42
	v_permlane32_swap_b32_e32 v205, v43
	v_permlane32_swap_b32_e32 v206, v44
	v_permlane32_swap_b32_e32 v207, v45
	v_sub_u32_e32 v203, v57, v202
	global_store_dwordx4 v203, v[204:207], s[72:73]
	global_store_dwordx4 v203, v[42:45], s[72:73] offset:64
	s_nop 1
	v_pk_mul_f32 v[46:47], v[38:39], v[52:53] op_sel_hi:[1,0]
	v_pk_mul_f32 v[38:39], v[40:41], v[52:53] op_sel_hi:[1,0]
	v_add_u32_e32 v48, v122, v56
	v_pk_mul_f32 v[38:39], v[184:185], v[38:39]
	v_pk_mul_f32 v[40:41], v[186:187], v[46:47]
	v_mov_b32_e32 v204, v38
	v_mov_b32_e32 v205, v39
	v_mov_b32_e32 v206, v40
	v_mov_b32_e32 v207, v41
	v_pk_mul_f32 v[32:33], v[188:189], v[32:33]
	v_pk_mul_f32 v[34:35], v[190:191], v[34:35]
	s_nop 1
	v_permlane16_swap_b32_e32 v204, v32
	v_permlane16_swap_b32_e32 v205, v33
	v_permlane16_swap_b32_e32 v206, v34
	v_permlane16_swap_b32_e32 v207, v35
	v_permlane32_swap_b32_e32 v204, v32
	v_permlane32_swap_b32_e32 v205, v33
	v_permlane32_swap_b32_e32 v206, v34
	v_permlane32_swap_b32_e32 v207, v35
	v_sub_u32_e32 v203, v48, v202
	global_store_dwordx4 v203, v[204:207], s[72:73]
	global_store_dwordx4 v203, v[32:35], s[72:73] offset:64
	s_nop 1
	s_nop 0
	v_lshlrev_b32_e32 v40, 12, v36
	v_add_u32_e32 v41, v40, v141
	v_fmamk_f32 v37, v198, 0x3a800000, v163
	v_mul_f32_e32 v38, 0x4b800000, v37
	v_cmp_gt_f32_e32 vcc, s51, v37
	s_nop 1
	v_cndmask_b32_e32 v37, v37, v38, vcc
	v_rsq_f32_e32 v37, v37
	s_nop 0
	v_mul_f32_e32 v36, 0x45800000, v37
	v_cndmask_b32_e32 v36, v37, v36, vcc
; #define BAR __builtin_amdgcn_s_barrier()
; #define BAR do { __builtin_amdgcn_sched_barrier(0); __builtin_amdgcn_s_barrier(); asm volatile("" ::: "memory"); __builtin_amdgcn_sched_barrier(0); } while (0)
; template <bool SP2, bool ALIGN_EPI, bool DUAL, class Epi> DI void gemm_phase2(const bf16_t* A, const bf16_t* Bt, const bf16_t* A2, const bf16_t* Bt2, int M, int N, int K, const Epi& E, lds_t* lds) {
;     ...
;     if (!has_next) break;
;     if (!(DUAL && pass == 0)) { zero_acc(acc); ++ui; }
;     pm = npm; pn = npn; cA = nA; cB = nB; pass = npass;
;     if constexpr (ALIGN_EPI) { if (wr == 1) BAR; }
;   DI void operator()(g8::Acc& acc, int pm, int pn, int wr, int wc, int fr, int fq) const {
;     ...
;     for (int ai = 0; ai < 2; ++ai)
; #pragma unroll
;       for (int m = 0; m < 4; ++m) {
;         const int row = pm * BM + ai * HALF + wr * 64 + m * 16 + fr;
;         const float rs = rsqrtf(__hip_atomic_load(ssq + row, __ATOMIC_RELAXED, __HIP_MEMORY_SCOPE_AGENT) * (1.0f / DM) + RMS_EPS);
; #pragma unroll
;         for (int bj = 0; bj < 2; ++bj) {
;           const int col8 = pn * BM + wc * 64 + bj * 32 + fq * 8; const unsigned eo = (unsigned)row * DM + (unsigned)col8;
;           gst<f32x4>(outf, eo * 4u, acc[ai][bj][m][0] * rs * gld<f32x4>(g, (unsigned)col8 * 4u));
;           gst<f32x4>(outf, eo * 4u + 16u, acc[ai][bj][m][1] * rs * gld<f32x4>(g, (unsigned)col8 * 4u + 16u));
;         }
;       }
	v_pk_mul_f32 v[38:39], v[154:155], v[36:37] op_sel_hi:[1,0]
	v_pk_mul_f32 v[30:31], v[30:31], v[36:37] op_sel_hi:[1,0]
	v_pk_mul_f32 v[32:33], v[176:177], v[38:39]
	v_pk_mul_f32 v[34:35], v[178:179], v[30:31]
	v_mov_b32_e32 v204, v32
	v_mov_b32_e32 v205, v33
	v_mov_b32_e32 v206, v34
	v_mov_b32_e32 v207, v35
	v_pk_mul_f32 v[18:19], v[18:19], v[36:37] op_sel_hi:[1,0]
	v_pk_mul_f32 v[34:35], v[26:27], v[36:37] op_sel_hi:[1,0]
	v_pk_mul_f32 v[26:27], v[28:29], v[36:37] op_sel_hi:[1,0]
	v_pk_mul_f32 v[16:17], v[16:17], v[36:37] op_sel_hi:[1,0]
	v_pk_mul_f32 v[26:27], v[180:181], v[26:27]
	v_pk_mul_f32 v[28:29], v[182:183], v[34:35]
	s_nop 1
	v_permlane16_swap_b32_e32 v204, v26
	v_permlane16_swap_b32_e32 v205, v27
	v_permlane16_swap_b32_e32 v206, v28
	v_permlane16_swap_b32_e32 v207, v29
	v_permlane32_swap_b32_e32 v204, v26
	v_permlane32_swap_b32_e32 v205, v27
	v_permlane32_swap_b32_e32 v206, v28
	v_permlane32_swap_b32_e32 v207, v29
	v_sub_u32_e32 v203, v41, v202
	global_store_dwordx4 v203, v[204:207], s[72:73]
	global_store_dwordx4 v203, v[26:29], s[72:73] offset:64
	s_nop 1
	v_pk_mul_f32 v[30:31], v[22:23], v[36:37] op_sel_hi:[1,0]
	v_pk_mul_f32 v[22:23], v[24:25], v[36:37] op_sel_hi:[1,0]
	v_add_u32_e32 v32, v122, v40
	v_pk_mul_f32 v[22:23], v[184:185], v[22:23]
	v_pk_mul_f32 v[24:25], v[186:187], v[30:31]
	v_mov_b32_e32 v204, v22
	v_mov_b32_e32 v205, v23
	v_mov_b32_e32 v206, v24
	v_mov_b32_e32 v207, v25
	v_pk_mul_f32 v[16:17], v[188:189], v[16:17]
	v_pk_mul_f32 v[18:19], v[190:191], v[18:19]
	s_nop 1
	v_permlane16_swap_b32_e32 v204, v16
	v_permlane16_swap_b32_e32 v205, v17
	v_permlane16_swap_b32_e32 v206, v18
	v_permlane16_swap_b32_e32 v207, v19
	v_permlane32_swap_b32_e32 v204, v16
	v_permlane32_swap_b32_e32 v205, v17
	v_permlane32_swap_b32_e32 v206, v18
	v_permlane32_swap_b32_e32 v207, v19
	v_sub_u32_e32 v203, v32, v202
	global_store_dwordx4 v203, v[204:207], s[72:73]
	global_store_dwordx4 v203, v[16:19], s[72:73] offset:64
	s_nop 1
	s_nop 0
	v_fmamk_f32 v21, v199, 0x3a800000, v163
	v_mul_f32_e32 v22, 0x4b800000, v21
	v_cmp_gt_f32_e32 vcc, s51, v21
	s_nop 1
	v_cndmask_b32_e32 v21, v21, v22, vcc
	v_rsq_f32_e32 v21, v21
	v_lshlrev_b32_e32 v22, 12, v20
	v_add_u32_e32 v23, v22, v141
	v_mul_f32_e32 v20, 0x45800000, v21
	v_cndmask_b32_e32 v20, v21, v20, vcc
	v_pk_mul_f32 v[12:13], v[12:13], v[20:21] op_sel_hi:[1,0]
	v_pk_mul_f32 v[14:15], v[14:15], v[20:21] op_sel_hi:[1,0]
	v_pk_mul_f32 v[12:13], v[176:177], v[12:13]
	v_pk_mul_f32 v[14:15], v[178:179], v[14:15]
	v_mov_b32_e32 v204, v12
	v_mov_b32_e32 v205, v13
	v_mov_b32_e32 v206, v14
	v_mov_b32_e32 v207, v15
	v_pk_mul_f32 v[10:11], v[10:11], v[20:21] op_sel_hi:[1,0]
	v_pk_mul_f32 v[8:9], v[8:9], v[20:21] op_sel_hi:[1,0]
	v_pk_mul_f32 v[6:7], v[6:7], v[20:21] op_sel_hi:[1,0]
	v_pk_mul_f32 v[4:5], v[4:5], v[20:21] op_sel_hi:[1,0]
	v_pk_mul_f32 v[2:3], v[2:3], v[20:21] op_sel_hi:[1,0]
	v_pk_mul_f32 v[0:1], v[0:1], v[20:21] op_sel_hi:[1,0]
	s_andn2_b64 vcc, exec, s[28:29]
	v_pk_mul_f32 v[8:9], v[180:181], v[8:9]
	v_pk_mul_f32 v[10:11], v[182:183], v[10:11]
	s_nop 1
	v_permlane16_swap_b32_e32 v204, v8
	v_permlane16_swap_b32_e32 v205, v9
	v_permlane16_swap_b32_e32 v206, v10
	v_permlane16_swap_b32_e32 v207, v11
	v_permlane32_swap_b32_e32 v204, v8
	v_permlane32_swap_b32_e32 v205, v9
	v_permlane32_swap_b32_e32 v206, v10
	v_permlane32_swap_b32_e32 v207, v11
	v_sub_u32_e32 v203, v23, v202
	global_store_dwordx4 v203, v[204:207], s[72:73]
	global_store_dwordx4 v203, v[8:11], s[72:73] offset:64
	s_nop 1
	v_add_u32_e32 v12, v122, v22
	v_pk_mul_f32 v[4:5], v[184:185], v[4:5]
	v_pk_mul_f32 v[6:7], v[186:187], v[6:7]
	v_mov_b32_e32 v204, v4
	v_mov_b32_e32 v205, v5
	v_mov_b32_e32 v206, v6
	v_mov_b32_e32 v207, v7
	v_pk_mul_f32 v[0:1], v[188:189], v[0:1]
	v_pk_mul_f32 v[2:3], v[190:191], v[2:3]
	s_nop 1
	v_permlane16_swap_b32_e32 v204, v0
	v_permlane16_swap_b32_e32 v205, v1
	v_permlane16_swap_b32_e32 v206, v2
	v_permlane16_swap_b32_e32 v207, v3
	v_permlane32_swap_b32_e32 v204, v0
	v_permlane32_swap_b32_e32 v205, v1
	v_permlane32_swap_b32_e32 v206, v2
	v_permlane32_swap_b32_e32 v207, v3
	v_sub_u32_e32 v203, v12, v202
	global_store_dwordx4 v203, v[204:207], s[72:73]
	global_store_dwordx4 v203, v[0:3], s[72:73] offset:64
	s_nop 1
	s_cbranch_vccnz .LBB0_892
	s_andn2_b64 vcc, exec, s[6:7]
	s_cbranch_vccnz .LBB0_891
	s_barrier
	s_branch .LBB0_891
